# placement: 64-byte alignment pins at the heads of the five GEMM K-loops, the prompt attention loop and the RG-LRU tile loop
# baseline (speedup 1.0000x reference)
.LBB0_87:
	s_ashr_i32 s89, s88, 31
	s_lshl_b64 s[10:11], s[88:89], 19
	s_add_u32 s90, s24, s10
	s_addc_u32 s91, s25, s11
	s_and_b64 s[10:11], s[2:3], exec
	s_cselect_b32 s5, s91, s7
	s_cselect_b32 s10, s90, s6
	s_ashr_i32 s87, s86, 31
	s_lshl_b64 s[26:27], s[86:87], 19
	s_add_u32 s92, s12, s26
	s_addc_u32 s93, s13, s27
	s_and_b64 s[26:27], s[2:3], exec
	s_cselect_b32 s11, s93, s9
	s_cselect_b32 s26, s92, s8
	s_add_u32 s6, s6, 0x40080
	s_addc_u32 s7, s7, 0
	s_add_u32 s27, s8, 0x100
	v_mov_b32_e32 v0, 0
	s_addc_u32 s53, s9, 0
	s_mov_b32 s54, -2
	v_mov_b32_e32 v1, v0
	v_mov_b32_e32 v2, v0
	v_mov_b32_e32 v3, v0
	v_mov_b32_e32 v4, v0
	v_mov_b32_e32 v5, v0
	v_mov_b32_e32 v6, v0
	v_mov_b32_e32 v7, v0
	v_mov_b32_e32 v16, v0
	v_mov_b32_e32 v17, v0
	v_mov_b32_e32 v18, v0
	v_mov_b32_e32 v19, v0
	v_mov_b32_e32 v20, v0
	v_mov_b32_e32 v21, v0
	v_mov_b32_e32 v22, v0
	v_mov_b32_e32 v23, v0
	v_mov_b32_e32 v32, v0
	v_mov_b32_e32 v33, v0
	v_mov_b32_e32 v34, v0
	v_mov_b32_e32 v35, v0
	v_mov_b32_e32 v36, v0
	v_mov_b32_e32 v37, v0
	v_mov_b32_e32 v38, v0
	v_mov_b32_e32 v39, v0
	v_mov_b32_e32 v48, v0
	v_mov_b32_e32 v49, v0
	v_mov_b32_e32 v50, v0
	v_mov_b32_e32 v51, v0
	v_mov_b32_e32 v52, v0
	v_mov_b32_e32 v53, v0
	v_mov_b32_e32 v54, v0
	v_mov_b32_e32 v55, v0
	v_mov_b32_e32 v8, v0
	v_mov_b32_e32 v9, v0
	v_mov_b32_e32 v10, v0
	v_mov_b32_e32 v11, v0
	v_mov_b32_e32 v12, v0
	v_mov_b32_e32 v13, v0
	v_mov_b32_e32 v14, v0
	v_mov_b32_e32 v15, v0
	v_mov_b32_e32 v24, v0
	v_mov_b32_e32 v25, v0
	v_mov_b32_e32 v26, v0
	v_mov_b32_e32 v27, v0
	v_mov_b32_e32 v28, v0
	v_mov_b32_e32 v29, v0
	v_mov_b32_e32 v30, v0
	v_mov_b32_e32 v31, v0
	v_mov_b32_e32 v40, v0
	v_mov_b32_e32 v41, v0
	v_mov_b32_e32 v42, v0
	v_mov_b32_e32 v43, v0
	v_mov_b32_e32 v44, v0
	v_mov_b32_e32 v45, v0
	v_mov_b32_e32 v46, v0
	v_mov_b32_e32 v47, v0
	v_mov_b32_e32 v56, v0
	v_mov_b32_e32 v57, v0
	v_mov_b32_e32 v58, v0
	v_mov_b32_e32 v59, v0
	v_mov_b32_e32 v60, v0
	v_mov_b32_e32 v61, v0
	v_mov_b32_e32 v62, v0
	v_mov_b32_e32 v63, v0
	v_mov_b32_e32 v64, v0
	v_mov_b32_e32 v65, v0
	v_mov_b32_e32 v66, v0
	v_mov_b32_e32 v67, v0
	v_mov_b32_e32 v68, v0
	v_mov_b32_e32 v69, v0
	v_mov_b32_e32 v70, v0
	v_mov_b32_e32 v71, v0
	v_mov_b32_e32 v80, v0
	v_mov_b32_e32 v81, v0
	v_mov_b32_e32 v82, v0
	v_mov_b32_e32 v83, v0
	v_mov_b32_e32 v84, v0
	v_mov_b32_e32 v85, v0
	v_mov_b32_e32 v86, v0
	v_mov_b32_e32 v87, v0
	v_mov_b32_e32 v96, v0
	v_mov_b32_e32 v97, v0
	v_mov_b32_e32 v98, v0
	v_mov_b32_e32 v99, v0
	v_mov_b32_e32 v100, v0
	v_mov_b32_e32 v101, v0
	v_mov_b32_e32 v102, v0
	v_mov_b32_e32 v103, v0
	v_mov_b32_e32 v112, v0
	v_mov_b32_e32 v113, v0
	v_mov_b32_e32 v114, v0
	v_mov_b32_e32 v115, v0
	v_mov_b32_e32 v116, v0
	v_mov_b32_e32 v117, v0
	v_mov_b32_e32 v118, v0
	v_mov_b32_e32 v119, v0
	v_mov_b32_e32 v72, v0
	v_mov_b32_e32 v73, v0
	v_mov_b32_e32 v74, v0
	v_mov_b32_e32 v75, v0
	v_mov_b32_e32 v76, v0
	v_mov_b32_e32 v77, v0
	v_mov_b32_e32 v78, v0
	v_mov_b32_e32 v79, v0
	v_mov_b32_e32 v88, v0
	v_mov_b32_e32 v89, v0
	v_mov_b32_e32 v90, v0
	v_mov_b32_e32 v91, v0
	v_mov_b32_e32 v92, v0
	v_mov_b32_e32 v93, v0
	v_mov_b32_e32 v94, v0
	v_mov_b32_e32 v95, v0
	v_mov_b32_e32 v104, v0
	v_mov_b32_e32 v105, v0
	v_mov_b32_e32 v106, v0
	v_mov_b32_e32 v107, v0
	v_mov_b32_e32 v108, v0
	v_mov_b32_e32 v109, v0
	v_mov_b32_e32 v110, v0
	v_mov_b32_e32 v111, v0
	v_mov_b32_e32 v120, v0
	v_mov_b32_e32 v121, v0
	v_mov_b32_e32 v122, v0
	v_mov_b32_e32 v123, v0
	v_mov_b32_e32 v124, v0
	v_mov_b32_e32 v125, v0
	v_mov_b32_e32 v126, v0
	v_mov_b32_e32 v127, v0
	.p2align	6

.LBB0_510:
	s_or_b64 exec, exec, vcc
	s_mov_b64 s[26:27], 0x50000
	s_add_i32 s57, s57, 64
	v_lshl_add_u64 v[32:33], v[32:33], 0, s[26:27]
	s_mov_b64 s[26:27], 0x20000
	v_fmac_f32_e32 v40, v20, v21
	v_lshl_add_u64 v[34:35], v[34:35], 0, s[90:91]
	s_cmpk_gt_u32 s57, 0x7bf
	v_lshl_add_u64 v[36:37], v[36:37], 0, s[26:27]
	s_cbranch_scc1 .LBB0_520
	.p2align	6

.LBB0_523:
	s_cmp_lt_i32 s4, 0
	s_cbranch_scc1 .LBB0_436
	v_mov_b32_e32 v1, v188
	v_mov_b32_e32 v3, v0
	v_readfirstlane_b32 s2, v1
	s_ashr_i32 s6, s2, 6
	s_andn2_b32 s2, s2, 63
	s_lshl_b32 s3, s2, 7
	s_add_i32 s7, s3, 0
	s_lshr_b32 s3, s4, 2
	s_lshl_b32 s4, s4, 5
	s_and_b32 s3, s3, 0x1ffffff8
	s_and_b32 s4, s4, 0x3e0
	s_or_b32 s4, s3, s4
	s_or_b32 s3, s3, s52
	s_lshl_b32 s3, s3, 11
	s_lshr_b32 s5, s4, 5
	s_and_b32 s3, s3, 0xf800
	s_lshl_b32 s8, s5, 6
	v_mul_u32_u24_e32 v2, s3, v196
	s_sub_i32 s8, s3, s8
	v_readfirstlane_b32 s3, v2
	s_add_i32 s62, s8, 0x7c0
	s_lshl_b32 s3, s3, 1
	s_add_u32 s10, s82, s3
	s_addc_u32 s11, s83, 0
	s_ashr_i32 s3, s2, 31
	s_lshl_b64 s[8:9], s[2:3], 1
	s_add_u32 s16, s10, s8
	s_addc_u32 s17, s11, s9
	s_mul_i32 s3, s62, 0x1400
	s_mul_hi_u32 s2, s62, 0x1400
	s_add_u32 s3, s82, s3
	s_addc_u32 s10, s83, s2
	v_and_b32_e32 v197, 15, v1
	s_add_u32 s2, s3, s8
	v_mul_u32_u24_e32 v2, 0x1400, v197
	s_addc_u32 s3, s10, s9
	v_and_or_b32 v2, v1, 48, v2
	v_lshl_add_u64 v[4:5], s[2:3], 0, v[2:3]
	global_load_dwordx4 v[50:53], v2, s[2:3] offset:2048
	global_load_dwordx4 v[54:57], v2, s[2:3] offset:2112
	v_add_co_u32_e32 v2, vcc, s50, v4
	s_lshl_b32 s10, s5, 1
	s_nop 0
	v_addc_co_u32_e32 v3, vcc, 0, v5, vcc
	s_mov_b32 s2, 0x28000
	s_sub_i32 s10, s10, 46
	global_load_dwordx4 v[58:61], v[2:3], off offset:2048
	global_load_dwordx4 v[62:65], v[2:3], off offset:2112
	v_add_co_u32_e32 v2, vcc, s2, v4
	s_cmpk_gt_u32 s4, 0x2ff
	s_nop 0
	v_addc_co_u32_e32 v3, vcc, 0, v5, vcc
	s_mov_b32 s2, 0x3c000
	s_cselect_b32 s12, s10, 0
	global_load_dwordx4 v[66:69], v[2:3], off offset:2048
	global_load_dwordx4 v[70:73], v[2:3], off offset:2112
	v_add_co_u32_e32 v2, vcc, s2, v4
	s_sub_i32 s2, 23, s5
	s_ashr_i32 s3, s2, 31
	s_lshl_b64 s[10:11], s[2:3], 6
	s_lshl_b32 s13, s12, 5
	s_add_u32 s2, s10, s13
	s_addc_u32 s3, s11, 0
	s_mulk_i32 s3, 0x1400
	s_mul_hi_u32 s4, s2, 0x1400
	s_add_i32 s4, s4, s3
	s_mulk_i32 s2, 0x1400
	v_addc_co_u32_e32 v3, vcc, 0, v5, vcc
	v_bfe_u32 v6, v1, 4, 2
	s_add_u32 s2, s16, s2
	global_load_dwordx4 v[74:77], v[2:3], off offset:2048
	global_load_dwordx4 v[78:81], v[2:3], off offset:2112
	s_addc_u32 s3, s17, s4
	v_mul_u32_u24_e32 v2, 0xa00, v197
	v_lshlrev_b32_e32 v198, 3, v6
	s_add_u32 s4, s2, 0xc00
	v_or_b32_e32 v2, v198, v2
	s_addc_u32 s5, s3, 0
	v_lshlrev_b32_e32 v154, 1, v2
	v_mov_b32_e32 v155, v0
	v_lshl_add_u64 v[2:3], s[4:5], 0, v[154:155]
	v_add_co_u32_e32 v2, vcc, s50, v2
	v_bfe_u32 v4, v1, 3, 3
	s_nop 0
	v_addc_co_u32_e32 v3, vcc, 0, v3, vcc
	v_mul_u32_u24_e32 v5, 0x1400, v4
	global_load_dwordx4 v[122:125], v154, s[2:3] offset:3072
	global_load_dwordx4 v[118:121], v154, s[2:3] offset:3136
	global_load_dwordx4 v[146:149], v[2:3], off
	global_load_dwordx4 v[114:117], v[2:3], off offset:64
	v_bitop3_b32 v2, v4, v1, 7 bitop3:0x78
	v_lshl_or_b32 v156, v2, 4, v5
	v_mov_b32_e32 v157, v0
	v_lshl_add_u64 v[2:3], s[4:5], 0, v[156:157]
	s_waitcnt lgkmcnt(0)
	v_lshl_add_u64 v[4:5], v[2:3], 0, s[92:93]
	s_mov_b32 m0, s7
	v_and_b32_e32 v199, 63, v1
	global_load_lds_dwordx4 v[4:5], off
	v_lshl_add_u64 v[4:5], v[2:3], 0, s[94:95]
	s_add_i32 m0, s7, 0x400
	s_mul_i32 s2, s6, 0x500
	global_load_lds_dwordx4 v[4:5], off
	v_lshl_add_u64 v[4:5], v[2:3], 0, s[96:97]
	s_add_i32 m0, s7, 0x800
	v_lshl_add_u64 v[2:3], v[2:3], 0, s[60:61]
	global_load_lds_dwordx4 v[4:5], off
	s_add_i32 m0, s7, 0xc00
	v_bfe_u32 v4, v1, 1, 1
	global_load_lds_dwordx4 v[2:3], off
	v_bfe_u32 v2, v1, 2, 2
	v_lshlrev_b32_e32 v3, 2, v6
	v_lshlrev_b32_e32 v1, 3, v1
	v_or_b32_e32 v2, v3, v2
	v_and_b32_e32 v1, 8, v1
	v_lshl_or_b32 v200, v2, 7, v1
	v_bitop3_b32 v1, v2, v4, 7 bitop3:0x6c
	v_lshlrev_b32_e32 v201, 4, v1
	v_or_b32_e32 v1, 2, v4
	v_bitop3_b32 v1, v2, v1, 7 bitop3:0x6c
	v_lshlrev_b32_e32 v202, 4, v1
	v_or_b32_e32 v1, 4, v4
	v_bitop3_b32 v1, v2, v1, 7 bitop3:0x6c
	v_lshlrev_b32_e32 v203, 4, v1
	v_or_b32_e32 v1, 6, v4
	v_bitop3_b32 v1, v2, v1, 7 bitop3:0x6c
	v_lshlrev_b32_e32 v204, 4, v1
	v_sub_u32_e32 v1, v197, v3
	s_add_i32 s18, s2, 0
	v_subrev_u32_e32 v1, s13, v1
	s_add_i32 s2, s18, 0x209b4
	v_mov_b32_e32 v90, v0
	v_mov_b32_e32 v91, v0
	v_mov_b32_e32 v92, v0
	v_mov_b32_e32 v93, v0
	v_lshl_add_u32 v205, v1, 2, s2
	v_mov_b32_e32 v1, v0
	v_mov_b64_e32 v[46:47], v[90:91]
	v_mov_b64_e32 v[30:31], v[90:91]
	v_mov_b64_e32 v[14:15], v[90:91]
	v_mov_b64_e32 v[96:97], v[92:93]
	v_mov_b64_e32 v[42:43], v[90:91]
	v_mov_b64_e32 v[26:27], v[90:91]
	v_mov_b64_e32 v[10:11], v[90:91]
	v_mov_b64_e32 v[86:87], v[90:91]
	v_mov_b64_e32 v[38:39], v[90:91]
	v_mov_b64_e32 v[22:23], v[90:91]
	v_mov_b64_e32 v[6:7], v[90:91]
	v_mov_b64_e32 v[82:83], v[90:91]
	v_mov_b64_e32 v[34:35], v[90:91]
	s_waitcnt lgkmcnt(0)
	v_mov_b64_e32 v[18:19], v[90:91]
	v_mov_b64_e32 v[2:3], v[90:91]
	s_or_b32 s19, s13, 32
	s_add_i32 s20, s12, -1
	v_mov_b32_e32 v206, 0xff800000
	v_mov_b32_e32 v207, 0xff800000
	v_mov_b32_e32 v208, 0xff800000
	v_mov_b32_e32 v209, 0xff800000
	v_mov_b64_e32 v[48:49], v[92:93]
	v_mov_b64_e32 v[32:33], v[92:93]
	v_mov_b64_e32 v[16:17], v[92:93]
	v_mov_b64_e32 v[94:95], v[90:91]
	v_mov_b64_e32 v[44:45], v[92:93]
	s_waitcnt vmcnt(0)
	v_mov_b64_e32 v[102:103], v[122:123]
	v_mov_b64_e32 v[110:111], v[146:147]
	v_mov_b64_e32 v[106:107], v[114:115]
	v_mov_b64_e32 v[98:99], v[118:119]
	v_mov_b64_e32 v[28:29], v[92:93]
	v_mov_b64_e32 v[12:13], v[92:93]
	v_mov_b64_e32 v[88:89], v[92:93]
	v_mov_b64_e32 v[40:41], v[92:93]
	v_mov_b64_e32 v[24:25], v[92:93]
	v_mov_b64_e32 v[8:9], v[92:93]
	v_mov_b64_e32 v[84:85], v[92:93]
	v_mov_b64_e32 v[36:37], v[92:93]
	v_mov_b64_e32 v[20:21], v[92:93]
	v_mov_b64_e32 v[4:5], v[92:93]
	v_mov_b64_e32 v[150:151], v[0:1]
	v_mov_b64_e32 v[152:153], v[0:1]
	v_mov_b64_e32 v[108:109], v[116:117]
	v_mov_b64_e32 v[112:113], v[148:149]
	v_mov_b64_e32 v[100:101], v[120:121]
	v_mov_b64_e32 v[104:105], v[124:125]
	.p2align	6

.LBB0_630:
	v_add_u32_e32 v1, s47, v158
	ds_read_b128 v[174:177], v1
	ds_read_b128 v[178:181], v1 offset:1024
	ds_read_b128 v[182:185], v1 offset:2048
	ds_read_b128 v[190:193], v1 offset:3072
	v_add_u32_e32 v1, s48, v158
	s_add_u32 s53, s58, s54
	ds_read_b128 v[194:197], v1
	ds_read_b128 v[198:201], v1 offset:1024
	ds_read_b128 v[202:205], v1 offset:2048
	ds_read_b128 v[206:209], v1 offset:3072
	s_addc_u32 s57, s59, s55
	s_add_u32 s53, s53, 0x100
	s_addc_u32 s57, s57, 0
	s_add_u32 s60, s50, s54
	s_addc_u32 s61, s51, s55
	s_cmpk_eq_i32 s54, 0x700
	s_cselect_b32 s63, s21, s57
	s_cselect_b32 s62, s26, s53
	s_cselect_b32 s61, s19, s61
	s_cselect_b32 s60, s27, s60
	v_lshl_add_u64 v[2:3], v[148:149], 0, s[54:55]
	s_add_i32 m0, s38, 0xc000
	ds_read_b128 v[210:213], v169
	ds_read_b128 v[214:217], v169 offset:1024
	ds_read_b128 v[218:221], v169 offset:2048
	ds_read_b128 v[222:225], v169 offset:3072
	ds_read_b128 v[226:229], v169 offset:4096
	ds_read_b128 v[230:233], v169 offset:5120
	ds_read_b128 v[234:237], v169 offset:6144
	ds_read_b128 v[238:241], v169 offset:7168
	global_load_lds_dwordx4 v[2:3], off
	v_lshl_add_u64 v[2:3], v[150:151], 0, s[54:55]
	s_add_i32 m0, s38, 0xe000
	s_nop 0
	global_load_lds_dwordx4 v[2:3], off
	s_waitcnt vmcnt(8)
	s_waitcnt lgkmcnt(0)
	s_barrier
	s_setprio 1
	s_waitcnt lgkmcnt(0)
	v_mfma_f32_16x16x32_bf16 v[128:131], v[174:177], v[210:213], v[128:131]
	v_mfma_f32_16x16x32_bf16 v[124:127], v[182:185], v[210:213], v[124:127]
	v_mfma_f32_16x16x32_bf16 v[112:115], v[174:177], v[218:221], v[112:115]
	v_mfma_f32_16x16x32_bf16 v[108:111], v[182:185], v[218:221], v[108:111]
	v_mfma_f32_16x16x32_bf16 v[96:99], v[174:177], v[226:229], v[96:99]
	v_mfma_f32_16x16x32_bf16 v[92:95], v[182:185], v[226:229], v[92:95]
	v_mfma_f32_16x16x32_bf16 v[80:83], v[174:177], v[234:237], v[80:83]
	v_mfma_f32_16x16x32_bf16 v[76:79], v[182:185], v[234:237], v[76:79]
	v_mfma_f32_16x16x32_bf16 v[128:131], v[178:181], v[214:217], v[128:131]
	v_mfma_f32_16x16x32_bf16 v[124:127], v[190:193], v[214:217], v[124:127]
	v_mfma_f32_16x16x32_bf16 v[112:115], v[178:181], v[222:225], v[112:115]
	v_mfma_f32_16x16x32_bf16 v[108:111], v[190:193], v[222:225], v[108:111]
	v_mfma_f32_16x16x32_bf16 v[96:99], v[178:181], v[230:233], v[96:99]
	v_mfma_f32_16x16x32_bf16 v[92:95], v[190:193], v[230:233], v[92:95]
	v_mfma_f32_16x16x32_bf16 v[80:83], v[178:181], v[238:241], v[80:83]
	v_mfma_f32_16x16x32_bf16 v[76:79], v[190:193], v[238:241], v[76:79]
	s_setprio 0
	s_setprio 1
	v_mfma_f32_16x16x32_bf16 v[120:123], v[194:197], v[210:213], v[120:123]
	v_mfma_f32_16x16x32_bf16 v[116:119], v[202:205], v[210:213], v[116:119]
	v_mfma_f32_16x16x32_bf16 v[104:107], v[194:197], v[218:221], v[104:107]
	v_mfma_f32_16x16x32_bf16 v[100:103], v[202:205], v[218:221], v[100:103]
	v_mfma_f32_16x16x32_bf16 v[88:91], v[194:197], v[226:229], v[88:91]
	v_mfma_f32_16x16x32_bf16 v[84:87], v[202:205], v[226:229], v[84:87]
	v_mfma_f32_16x16x32_bf16 v[72:75], v[194:197], v[234:237], v[72:75]
	v_mfma_f32_16x16x32_bf16 v[68:71], v[202:205], v[234:237], v[68:71]
	v_mfma_f32_16x16x32_bf16 v[120:123], v[198:201], v[214:217], v[120:123]
	v_mfma_f32_16x16x32_bf16 v[116:119], v[206:209], v[214:217], v[116:119]
	v_mfma_f32_16x16x32_bf16 v[104:107], v[198:201], v[222:225], v[104:107]
	v_mfma_f32_16x16x32_bf16 v[100:103], v[206:209], v[222:225], v[100:103]
	v_mfma_f32_16x16x32_bf16 v[88:91], v[198:201], v[230:233], v[88:91]
	v_mfma_f32_16x16x32_bf16 v[84:87], v[206:209], v[230:233], v[84:87]
	v_mfma_f32_16x16x32_bf16 v[72:75], v[198:201], v[238:241], v[72:75]
	v_mfma_f32_16x16x32_bf16 v[68:71], v[206:209], v[238:241], v[68:71]
	s_setprio 0
	s_barrier
	s_add_i32 s53, s47, s33
	v_lshl_add_u64 v[186:187], s[60:61], 0, v[134:135]
	s_mov_b32 m0, s53
	ds_read_b128 v[210:213], v169 offset:16384
	ds_read_b128 v[214:217], v169 offset:17408
	ds_read_b128 v[218:221], v169 offset:18432
	ds_read_b128 v[222:225], v169 offset:19456
	ds_read_b128 v[226:229], v169 offset:20480
	ds_read_b128 v[230:233], v169 offset:21504
	ds_read_b128 v[234:237], v169 offset:22528
	ds_read_b128 v[238:241], v169 offset:23552
	global_load_lds_dwordx4 v[186:187], off
	s_add_i32 m0, s53, 0x2000
	s_add_u32 s64, s60, 0x40000
	v_lshl_add_u64 v[242:243], s[60:61], 0, v[138:139]
	s_addc_u32 s65, s61, 0
	s_add_i32 s53, s48, s33
	global_load_lds_dwordx4 v[242:243], off
	v_lshl_add_u64 v[2:3], s[64:65], 0, v[134:135]
	s_mov_b32 m0, s53
	v_lshl_add_u64 v[244:245], s[62:63], 0, v[132:133]
	global_load_lds_dwordx4 v[2:3], off
	v_lshl_add_u64 v[2:3], s[64:65], 0, v[138:139]
	s_add_i32 m0, s53, 0x2000
	v_lshl_add_u64 v[246:247], s[62:63], 0, v[136:137]
	global_load_lds_dwordx4 v[2:3], off
	s_mov_b32 m0, s38
	s_nop 0
	global_load_lds_dwordx4 v[244:245], off
	s_mov_b32 m0, s39
	s_nop 0
	global_load_lds_dwordx4 v[246:247], off
	s_waitcnt vmcnt(8)
	s_waitcnt lgkmcnt(0)
	s_barrier
	s_setprio 1
	s_waitcnt lgkmcnt(0)
	v_mfma_f32_16x16x32_bf16 v[64:67], v[174:177], v[210:213], v[64:67]
	v_mfma_f32_16x16x32_bf16 v[60:63], v[182:185], v[210:213], v[60:63]
	v_mfma_f32_16x16x32_bf16 v[48:51], v[174:177], v[218:221], v[48:51]
	v_mfma_f32_16x16x32_bf16 v[44:47], v[182:185], v[218:221], v[44:47]
	v_mfma_f32_16x16x32_bf16 v[32:35], v[174:177], v[226:229], v[32:35]
	v_mfma_f32_16x16x32_bf16 v[28:31], v[182:185], v[226:229], v[28:31]
	v_mfma_f32_16x16x32_bf16 v[16:19], v[174:177], v[234:237], v[16:19]
	v_mfma_f32_16x16x32_bf16 v[12:15], v[182:185], v[234:237], v[12:15]
	v_mfma_f32_16x16x32_bf16 v[64:67], v[178:181], v[214:217], v[64:67]
	v_mfma_f32_16x16x32_bf16 v[60:63], v[190:193], v[214:217], v[60:63]
	v_mfma_f32_16x16x32_bf16 v[48:51], v[178:181], v[222:225], v[48:51]
	v_mfma_f32_16x16x32_bf16 v[44:47], v[190:193], v[222:225], v[44:47]
	v_mfma_f32_16x16x32_bf16 v[32:35], v[178:181], v[230:233], v[32:35]
	v_mfma_f32_16x16x32_bf16 v[28:31], v[190:193], v[230:233], v[28:31]
	v_mfma_f32_16x16x32_bf16 v[16:19], v[178:181], v[238:241], v[16:19]
	v_mfma_f32_16x16x32_bf16 v[12:15], v[190:193], v[238:241], v[12:15]
	s_setprio 0
	s_setprio 1
	v_mfma_f32_16x16x32_bf16 v[56:59], v[194:197], v[210:213], v[56:59]
	v_mfma_f32_16x16x32_bf16 v[52:55], v[202:205], v[210:213], v[52:55]
	v_mfma_f32_16x16x32_bf16 v[40:43], v[194:197], v[218:221], v[40:43]
	v_mfma_f32_16x16x32_bf16 v[36:39], v[202:205], v[218:221], v[36:39]
	v_mfma_f32_16x16x32_bf16 v[24:27], v[194:197], v[226:229], v[24:27]
	v_mfma_f32_16x16x32_bf16 v[20:23], v[202:205], v[226:229], v[20:23]
	v_mfma_f32_16x16x32_bf16 v[8:11], v[194:197], v[234:237], v[8:11]
	v_mfma_f32_16x16x32_bf16 v[2:5], v[202:205], v[234:237], v[4:7]
	v_mfma_f32_16x16x32_bf16 v[56:59], v[198:201], v[214:217], v[56:59]
	v_mfma_f32_16x16x32_bf16 v[52:55], v[206:209], v[214:217], v[52:55]
	v_mfma_f32_16x16x32_bf16 v[40:43], v[198:201], v[222:225], v[40:43]
	v_mfma_f32_16x16x32_bf16 v[36:39], v[206:209], v[222:225], v[36:39]
	v_mfma_f32_16x16x32_bf16 v[24:27], v[198:201], v[230:233], v[24:27]
	v_mfma_f32_16x16x32_bf16 v[20:23], v[206:209], v[230:233], v[20:23]
	v_mfma_f32_16x16x32_bf16 v[8:11], v[198:201], v[238:241], v[8:11]
	v_mfma_f32_16x16x32_bf16 v[2:5], v[206:209], v[238:241], v[2:5]
	s_setprio 0
	s_barrier
	s_add_i32 s53, 0, 0x18000
	v_add_u32_e32 v1, s53, v158
	s_add_i32 s57, 0, 0x1c000
	ds_read_b128 v[174:177], v1
	ds_read_b128 v[178:181], v1 offset:1024
	ds_read_b128 v[182:185], v1 offset:2048
	ds_read_b128 v[190:193], v1 offset:3072
	v_add_u32_e32 v1, s57, v158
	ds_read_b128 v[194:197], v1
	ds_read_b128 v[198:201], v1 offset:1024
	ds_read_b128 v[202:205], v1 offset:2048
	ds_read_b128 v[206:209], v1 offset:3072
	s_add_u32 s62, s62, 0x40000
	s_addc_u32 s63, s63, 0
	s_mov_b32 m0, s40
	v_lshl_add_u64 v[6:7], s[62:63], 0, v[132:133]
	ds_read_b128 v[210:213], v169 offset:32768
	ds_read_b128 v[214:217], v169 offset:33792
	ds_read_b128 v[218:221], v169 offset:34816
	ds_read_b128 v[222:225], v169 offset:35840
	ds_read_b128 v[226:229], v169 offset:36864
	ds_read_b128 v[230:233], v169 offset:37888
	ds_read_b128 v[234:237], v169 offset:38912
	ds_read_b128 v[238:241], v169 offset:39936
	global_load_lds_dwordx4 v[6:7], off
	v_lshl_add_u64 v[6:7], s[62:63], 0, v[136:137]
	s_mov_b32 m0, s41
	s_nop 0
	global_load_lds_dwordx4 v[6:7], off
	s_waitcnt vmcnt(8)
	s_waitcnt lgkmcnt(0)
	s_barrier
	s_setprio 1
	s_waitcnt lgkmcnt(0)
	v_mfma_f32_16x16x32_bf16 v[128:131], v[174:177], v[210:213], v[128:131]
	v_mfma_f32_16x16x32_bf16 v[124:127], v[182:185], v[210:213], v[124:127]
	v_mfma_f32_16x16x32_bf16 v[112:115], v[174:177], v[218:221], v[112:115]
	v_mfma_f32_16x16x32_bf16 v[108:111], v[182:185], v[218:221], v[108:111]
	v_mfma_f32_16x16x32_bf16 v[96:99], v[174:177], v[226:229], v[96:99]
	v_mfma_f32_16x16x32_bf16 v[92:95], v[182:185], v[226:229], v[92:95]
	v_mfma_f32_16x16x32_bf16 v[80:83], v[174:177], v[234:237], v[80:83]
	v_mfma_f32_16x16x32_bf16 v[76:79], v[182:185], v[234:237], v[76:79]
	v_mfma_f32_16x16x32_bf16 v[128:131], v[178:181], v[214:217], v[128:131]
	v_mfma_f32_16x16x32_bf16 v[124:127], v[190:193], v[214:217], v[124:127]
	v_mfma_f32_16x16x32_bf16 v[112:115], v[178:181], v[222:225], v[112:115]
	v_mfma_f32_16x16x32_bf16 v[108:111], v[190:193], v[222:225], v[108:111]
	v_mfma_f32_16x16x32_bf16 v[96:99], v[178:181], v[230:233], v[96:99]
	v_mfma_f32_16x16x32_bf16 v[92:95], v[190:193], v[230:233], v[92:95]
	v_mfma_f32_16x16x32_bf16 v[80:83], v[178:181], v[238:241], v[80:83]
	v_mfma_f32_16x16x32_bf16 v[76:79], v[190:193], v[238:241], v[76:79]
	s_setprio 0
	s_setprio 1
	v_mfma_f32_16x16x32_bf16 v[120:123], v[194:197], v[210:213], v[120:123]
	v_mfma_f32_16x16x32_bf16 v[116:119], v[202:205], v[210:213], v[116:119]
	v_mfma_f32_16x16x32_bf16 v[104:107], v[194:197], v[218:221], v[104:107]
	v_mfma_f32_16x16x32_bf16 v[100:103], v[202:205], v[218:221], v[100:103]
	v_mfma_f32_16x16x32_bf16 v[88:91], v[194:197], v[226:229], v[88:91]
	v_mfma_f32_16x16x32_bf16 v[84:87], v[202:205], v[226:229], v[84:87]
	v_mfma_f32_16x16x32_bf16 v[72:75], v[194:197], v[234:237], v[72:75]
	v_mfma_f32_16x16x32_bf16 v[68:71], v[202:205], v[234:237], v[68:71]
	v_mfma_f32_16x16x32_bf16 v[120:123], v[198:201], v[214:217], v[120:123]
	v_mfma_f32_16x16x32_bf16 v[116:119], v[206:209], v[214:217], v[116:119]
	v_mfma_f32_16x16x32_bf16 v[104:107], v[198:201], v[222:225], v[104:107]
	v_mfma_f32_16x16x32_bf16 v[100:103], v[206:209], v[222:225], v[100:103]
	v_mfma_f32_16x16x32_bf16 v[88:91], v[198:201], v[230:233], v[88:91]
	v_mfma_f32_16x16x32_bf16 v[84:87], v[206:209], v[230:233], v[84:87]
	v_mfma_f32_16x16x32_bf16 v[72:75], v[198:201], v[238:241], v[72:75]
	v_mfma_f32_16x16x32_bf16 v[68:71], v[206:209], v[238:241], v[68:71]
	s_setprio 0
	s_barrier
	s_add_i32 s53, s53, s33
	v_lshl_add_u64 v[6:7], v[186:187], 0, s[14:15]
	s_mov_b32 m0, s53
	ds_read_b128 v[210:213], v169 offset:49152
	ds_read_b128 v[214:217], v169 offset:50176
	ds_read_b128 v[218:221], v169 offset:51200
	ds_read_b128 v[222:225], v169 offset:52224
	ds_read_b128 v[226:229], v169 offset:53248
	ds_read_b128 v[230:233], v169 offset:54272
	ds_read_b128 v[234:237], v169 offset:55296
	ds_read_b128 v[238:241], v169 offset:56320
	global_load_lds_dwordx4 v[6:7], off
	s_add_i32 m0, s53, 0x2000
	s_add_u32 s60, s60, 0x40080
	v_lshl_add_u64 v[6:7], v[242:243], 0, s[14:15]
	s_addc_u32 s61, s61, 0
	s_add_i32 s53, s57, s33
	global_load_lds_dwordx4 v[6:7], off
	v_lshl_add_u64 v[6:7], s[60:61], 0, v[134:135]
	s_mov_b32 m0, s53
	s_nop 0
	global_load_lds_dwordx4 v[6:7], off
	v_lshl_add_u64 v[6:7], s[60:61], 0, v[138:139]
	s_add_i32 m0, s53, 0x2000
	s_nop 0
	global_load_lds_dwordx4 v[6:7], off
	v_lshl_add_u64 v[6:7], v[244:245], 0, s[14:15]
	s_mov_b32 m0, s42
	s_nop 0
	global_load_lds_dwordx4 v[6:7], off
	v_lshl_add_u64 v[6:7], v[246:247], 0, s[14:15]
	s_mov_b32 m0, s43
	s_nop 0
	global_load_lds_dwordx4 v[6:7], off
	s_waitcnt vmcnt(8)
	s_waitcnt lgkmcnt(0)
	s_barrier
	s_setprio 1
	s_waitcnt lgkmcnt(0)
	v_mfma_f32_16x16x32_bf16 v[64:67], v[174:177], v[210:213], v[64:67]
	v_mfma_f32_16x16x32_bf16 v[60:63], v[182:185], v[210:213], v[60:63]
	v_mfma_f32_16x16x32_bf16 v[48:51], v[174:177], v[218:221], v[48:51]
	v_mfma_f32_16x16x32_bf16 v[44:47], v[182:185], v[218:221], v[44:47]
	v_mfma_f32_16x16x32_bf16 v[32:35], v[174:177], v[226:229], v[32:35]
	v_mfma_f32_16x16x32_bf16 v[28:31], v[182:185], v[226:229], v[28:31]
	v_mfma_f32_16x16x32_bf16 v[16:19], v[174:177], v[234:237], v[16:19]
	v_mfma_f32_16x16x32_bf16 v[12:15], v[182:185], v[234:237], v[12:15]
	v_mfma_f32_16x16x32_bf16 v[64:67], v[178:181], v[214:217], v[64:67]
	v_mfma_f32_16x16x32_bf16 v[60:63], v[190:193], v[214:217], v[60:63]
	v_mfma_f32_16x16x32_bf16 v[48:51], v[178:181], v[222:225], v[48:51]
	v_mfma_f32_16x16x32_bf16 v[44:47], v[190:193], v[222:225], v[44:47]
	v_mfma_f32_16x16x32_bf16 v[32:35], v[178:181], v[230:233], v[32:35]
	v_mfma_f32_16x16x32_bf16 v[28:31], v[190:193], v[230:233], v[28:31]
	v_mfma_f32_16x16x32_bf16 v[16:19], v[178:181], v[238:241], v[16:19]
	v_mfma_f32_16x16x32_bf16 v[12:15], v[190:193], v[238:241], v[12:15]
	s_setprio 0
	s_setprio 1
	v_mfma_f32_16x16x32_bf16 v[56:59], v[194:197], v[210:213], v[56:59]
	v_mfma_f32_16x16x32_bf16 v[52:55], v[202:205], v[210:213], v[52:55]
	v_mfma_f32_16x16x32_bf16 v[40:43], v[194:197], v[218:221], v[40:43]
	v_mfma_f32_16x16x32_bf16 v[36:39], v[202:205], v[218:221], v[36:39]
	v_mfma_f32_16x16x32_bf16 v[24:27], v[194:197], v[226:229], v[24:27]
	v_mfma_f32_16x16x32_bf16 v[20:23], v[202:205], v[226:229], v[20:23]
	v_mfma_f32_16x16x32_bf16 v[6:9], v[194:197], v[234:237], v[8:11]
	v_mfma_f32_16x16x32_bf16 v[2:5], v[202:205], v[234:237], v[2:5]
	v_mfma_f32_16x16x32_bf16 v[56:59], v[198:201], v[214:217], v[56:59]
	v_mfma_f32_16x16x32_bf16 v[52:55], v[206:209], v[214:217], v[52:55]
	v_mfma_f32_16x16x32_bf16 v[40:43], v[198:201], v[222:225], v[40:43]
	v_mfma_f32_16x16x32_bf16 v[36:39], v[206:209], v[222:225], v[36:39]
	v_mfma_f32_16x16x32_bf16 v[24:27], v[198:201], v[230:233], v[24:27]
	v_mfma_f32_16x16x32_bf16 v[20:23], v[206:209], v[230:233], v[20:23]
	v_mfma_f32_16x16x32_bf16 v[8:11], v[198:201], v[238:241], v[6:9]
	v_mfma_f32_16x16x32_bf16 v[4:7], v[206:209], v[238:241], v[2:5]
	s_setprio 0
	s_barrier
	s_add_i32 s52, s52, 2
	s_add_u32 s54, s54, 0x100
	s_addc_u32 s55, s55, 0
	s_cmp_gt_u32 s52, 13
	s_cbranch_scc1 .LBB0_633
	.p2align	6

.LBB0_979:
	s_ashr_i32 s15, s14, 31
	s_lshl_b64 s[16:17], s[14:15], 19
	s_add_u32 s16, s25, s16
	s_addc_u32 s17, s26, s17
	s_and_b64 s[18:19], s[0:1], exec
	s_cselect_b32 s15, s17, s23
	s_cselect_b32 s51, s16, s22
	s_ashr_i32 s13, s12, 31
	s_lshl_b64 s[18:19], s[12:13], 19
	s_add_u32 s18, s27, s18
	s_addc_u32 s19, s33, s19
	s_and_b64 s[36:37], s[0:1], exec
	s_cselect_b32 s13, s19, s35
	s_cselect_b32 s52, s18, s34
	s_add_u32 s22, s22, 0x40080
	s_addc_u32 s23, s23, 0
	s_add_u32 s53, s34, 0x100
	v_mov_b32_e32 v4, 0
	s_addc_u32 s54, s35, 0
	s_mov_b32 s55, -2
	v_mov_b32_e32 v5, v4
	v_mov_b32_e32 v6, v4
	v_mov_b32_e32 v7, v4
	v_mov_b32_e32 v12, v4
	v_mov_b32_e32 v13, v4
	v_mov_b32_e32 v14, v4
	v_mov_b32_e32 v15, v4
	s_waitcnt lgkmcnt(0)
	v_mov_b32_e32 v20, v4
	v_mov_b32_e32 v21, v4
	v_mov_b32_e32 v22, v4
	v_mov_b32_e32 v23, v4
	v_mov_b32_e32 v28, v4
	v_mov_b32_e32 v29, v4
	v_mov_b32_e32 v30, v4
	v_mov_b32_e32 v31, v4
	v_mov_b32_e32 v36, v4
	v_mov_b32_e32 v37, v4
	v_mov_b32_e32 v38, v4
	v_mov_b32_e32 v39, v4
	v_mov_b32_e32 v44, v4
	v_mov_b32_e32 v45, v4
	v_mov_b32_e32 v46, v4
	v_mov_b32_e32 v47, v4
	v_mov_b32_e32 v52, v4
	v_mov_b32_e32 v53, v4
	v_mov_b32_e32 v54, v4
	v_mov_b32_e32 v55, v4
	v_mov_b32_e32 v60, v4
	v_mov_b32_e32 v61, v4
	v_mov_b32_e32 v62, v4
	v_mov_b32_e32 v63, v4
	v_mov_b32_e32 v0, v4
	v_mov_b32_e32 v1, v4
	v_mov_b32_e32 v2, v4
	v_mov_b32_e32 v3, v4
	v_mov_b32_e32 v8, v4
	v_mov_b32_e32 v9, v4
	v_mov_b32_e32 v10, v4
	v_mov_b32_e32 v11, v4
	v_mov_b32_e32 v16, v4
	v_mov_b32_e32 v17, v4
	v_mov_b32_e32 v18, v4
	v_mov_b32_e32 v19, v4
	v_mov_b32_e32 v24, v4
	v_mov_b32_e32 v25, v4
	v_mov_b32_e32 v26, v4
	v_mov_b32_e32 v27, v4
	v_mov_b32_e32 v32, v4
	v_mov_b32_e32 v33, v4
	v_mov_b32_e32 v34, v4
	v_mov_b32_e32 v35, v4
	v_mov_b32_e32 v40, v4
	v_mov_b32_e32 v41, v4
	v_mov_b32_e32 v42, v4
	v_mov_b32_e32 v43, v4
	v_mov_b32_e32 v48, v4
	v_mov_b32_e32 v49, v4
	v_mov_b32_e32 v50, v4
	v_mov_b32_e32 v51, v4
	v_mov_b32_e32 v56, v4
	v_mov_b32_e32 v57, v4
	v_mov_b32_e32 v58, v4
	v_mov_b32_e32 v59, v4
	v_mov_b32_e32 v64, v4
	v_mov_b32_e32 v65, v4
	v_mov_b32_e32 v66, v4
	v_mov_b32_e32 v67, v4
	v_mov_b32_e32 v76, v4
	v_mov_b32_e32 v77, v4
	v_mov_b32_e32 v78, v4
	v_mov_b32_e32 v79, v4
	v_mov_b32_e32 v84, v4
	v_mov_b32_e32 v85, v4
	v_mov_b32_e32 v86, v4
	v_mov_b32_e32 v87, v4
	v_mov_b32_e32 v92, v4
	v_mov_b32_e32 v93, v4
	v_mov_b32_e32 v94, v4
	v_mov_b32_e32 v95, v4
	v_mov_b32_e32 v100, v4
	v_mov_b32_e32 v101, v4
	v_mov_b32_e32 v102, v4
	v_mov_b32_e32 v103, v4
	v_mov_b32_e32 v108, v4
	v_mov_b32_e32 v109, v4
	v_mov_b32_e32 v110, v4
	v_mov_b32_e32 v111, v4
	v_mov_b32_e32 v120, v4
	v_mov_b32_e32 v121, v4
	v_mov_b32_e32 v122, v4
	v_mov_b32_e32 v123, v4
	v_mov_b32_e32 v124, v4
	v_mov_b32_e32 v125, v4
	v_mov_b32_e32 v126, v4
	v_mov_b32_e32 v127, v4
	v_mov_b32_e32 v68, v4
	v_mov_b32_e32 v69, v4
	v_mov_b32_e32 v70, v4
	v_mov_b32_e32 v71, v4
	v_mov_b32_e32 v72, v4
	v_mov_b32_e32 v73, v4
	v_mov_b32_e32 v74, v4
	v_mov_b32_e32 v75, v4
	v_mov_b32_e32 v80, v4
	v_mov_b32_e32 v81, v4
	v_mov_b32_e32 v82, v4
	v_mov_b32_e32 v83, v4
	v_mov_b32_e32 v88, v4
	v_mov_b32_e32 v89, v4
	v_mov_b32_e32 v90, v4
	v_mov_b32_e32 v91, v4
	v_mov_b32_e32 v96, v4
	v_mov_b32_e32 v97, v4
	v_mov_b32_e32 v98, v4
	v_mov_b32_e32 v99, v4
	v_mov_b32_e32 v104, v4
	v_mov_b32_e32 v105, v4
	v_mov_b32_e32 v106, v4
	v_mov_b32_e32 v107, v4
	v_mov_b32_e32 v112, v4
	v_mov_b32_e32 v113, v4
	v_mov_b32_e32 v114, v4
	v_mov_b32_e32 v115, v4
	v_mov_b32_e32 v116, v4
	v_mov_b32_e32 v117, v4
	v_mov_b32_e32 v118, v4
	v_mov_b32_e32 v119, v4
	.p2align	6

.LBB0_1060:
	s_add_u32 s4, s36, 0xb0080
	s_addc_u32 s5, s37, 0
	s_add_u32 s23, s34, 0x100
	v_mov_b32_e32 v0, 0
	s_addc_u32 s27, s35, 0
	s_mov_b32 s58, -2
	v_mov_b32_e32 v1, v0
	v_mov_b32_e32 v2, v0
	v_mov_b32_e32 v3, v0
	v_mov_b32_e32 v4, v0
	v_mov_b32_e32 v5, v0
	v_mov_b32_e32 v6, v0
	v_mov_b32_e32 v7, v0
	v_mov_b32_e32 v16, v0
	v_mov_b32_e32 v17, v0
	v_mov_b32_e32 v18, v0
	s_waitcnt lgkmcnt(0)
	v_mov_b32_e32 v19, v0
	v_mov_b32_e32 v20, v0
	v_mov_b32_e32 v21, v0
	v_mov_b32_e32 v22, v0
	v_mov_b32_e32 v23, v0
	v_mov_b32_e32 v32, v0
	v_mov_b32_e32 v33, v0
	v_mov_b32_e32 v34, v0
	v_mov_b32_e32 v35, v0
	v_mov_b32_e32 v36, v0
	v_mov_b32_e32 v37, v0
	v_mov_b32_e32 v38, v0
	v_mov_b32_e32 v39, v0
	v_mov_b32_e32 v48, v0
	v_mov_b32_e32 v49, v0
	v_mov_b32_e32 v50, v0
	v_mov_b32_e32 v51, v0
	v_mov_b32_e32 v52, v0
	v_mov_b32_e32 v53, v0
	v_mov_b32_e32 v54, v0
	v_mov_b32_e32 v55, v0
	v_mov_b32_e32 v8, v0
	v_mov_b32_e32 v9, v0
	v_mov_b32_e32 v10, v0
	v_mov_b32_e32 v11, v0
	v_mov_b32_e32 v12, v0
	v_mov_b32_e32 v13, v0
	v_mov_b32_e32 v14, v0
	v_mov_b32_e32 v15, v0
	v_mov_b32_e32 v24, v0
	v_mov_b32_e32 v25, v0
	v_mov_b32_e32 v26, v0
	v_mov_b32_e32 v27, v0
	v_mov_b32_e32 v28, v0
	v_mov_b32_e32 v29, v0
	v_mov_b32_e32 v30, v0
	v_mov_b32_e32 v31, v0
	v_mov_b32_e32 v40, v0
	v_mov_b32_e32 v41, v0
	v_mov_b32_e32 v42, v0
	v_mov_b32_e32 v43, v0
	v_mov_b32_e32 v44, v0
	v_mov_b32_e32 v45, v0
	v_mov_b32_e32 v46, v0
	v_mov_b32_e32 v47, v0
	v_mov_b32_e32 v56, v0
	v_mov_b32_e32 v57, v0
	v_mov_b32_e32 v58, v0
	v_mov_b32_e32 v59, v0
	v_mov_b32_e32 v60, v0
	v_mov_b32_e32 v61, v0
	v_mov_b32_e32 v62, v0
	v_mov_b32_e32 v63, v0
	v_mov_b32_e32 v64, v0
	v_mov_b32_e32 v65, v0
	v_mov_b32_e32 v66, v0
	v_mov_b32_e32 v67, v0
	v_mov_b32_e32 v68, v0
	v_mov_b32_e32 v69, v0
	v_mov_b32_e32 v70, v0
	v_mov_b32_e32 v71, v0
	v_mov_b32_e32 v80, v0
	v_mov_b32_e32 v81, v0
	v_mov_b32_e32 v82, v0
	v_mov_b32_e32 v83, v0
	v_mov_b32_e32 v84, v0
	v_mov_b32_e32 v85, v0
	v_mov_b32_e32 v86, v0
	v_mov_b32_e32 v87, v0
	v_mov_b32_e32 v96, v0
	v_mov_b32_e32 v97, v0
	v_mov_b32_e32 v98, v0
	v_mov_b32_e32 v99, v0
	v_mov_b32_e32 v100, v0
	v_mov_b32_e32 v101, v0
	v_mov_b32_e32 v102, v0
	v_mov_b32_e32 v103, v0
	v_mov_b32_e32 v112, v0
	v_mov_b32_e32 v113, v0
	v_mov_b32_e32 v114, v0
	v_mov_b32_e32 v115, v0
	v_mov_b32_e32 v116, v0
	v_mov_b32_e32 v117, v0
	v_mov_b32_e32 v118, v0
	v_mov_b32_e32 v119, v0
	v_mov_b32_e32 v72, v0
	v_mov_b32_e32 v73, v0
	v_mov_b32_e32 v74, v0
	v_mov_b32_e32 v75, v0
	v_mov_b32_e32 v76, v0
	v_mov_b32_e32 v77, v0
	v_mov_b32_e32 v78, v0
	v_mov_b32_e32 v79, v0
	v_mov_b32_e32 v88, v0
	v_mov_b32_e32 v89, v0
	v_mov_b32_e32 v90, v0
	v_mov_b32_e32 v91, v0
	v_mov_b32_e32 v92, v0
	v_mov_b32_e32 v93, v0
	v_mov_b32_e32 v94, v0
	v_mov_b32_e32 v95, v0
	v_mov_b32_e32 v104, v0
	v_mov_b32_e32 v105, v0
	v_mov_b32_e32 v106, v0
	v_mov_b32_e32 v107, v0
	v_mov_b32_e32 v108, v0
	v_mov_b32_e32 v109, v0
	v_mov_b32_e32 v110, v0
	v_mov_b32_e32 v111, v0
	v_mov_b32_e32 v120, v0
	v_mov_b32_e32 v121, v0
	v_mov_b32_e32 v122, v0
	v_mov_b32_e32 v123, v0
	v_mov_b32_e32 v124, v0
	v_mov_b32_e32 v125, v0
	v_mov_b32_e32 v126, v0
	v_mov_b32_e32 v127, v0
	.p2align	6

.LBB0_1105:
	s_mul_hi_i32 s17, s42, 0x2e8ba2e9
	s_ashr_i32 s16, s17, 1
	s_lshr_b32 s20, s17, 31
	s_add_i32 s16, s16, s20
	s_mul_i32 s18, s16, 0xfffff500
	s_add_i32 s18, s26, s18
	s_ashr_i32 s19, s18, 31
	s_lshl_b64 s[18:19], s[18:19], 1
	s_add_u32 s46, s24, s18
	s_addc_u32 s49, s25, s19
	s_add_u32 s18, s33, s18
	s_addc_u32 s19, s38, s19
	s_ashr_i32 s17, s17, 3
	s_add_i32 s44, s17, s20
	s_ashr_i32 s17, s16, 31
	s_lshr_b32 s17, s17, 30
	s_add_i32 s17, s16, s17
	s_and_b32 s17, s17, -4
	s_sub_i32 s45, s16, s17
	v_readfirstlane_b32 s43, v188
	s_lshr_b32 s48, s43, 6
	s_mul_i32 s20, s45, 0x160000
	s_addk_i32 s44, 0x100
	s_lshr_b32 s47, s43, 8
	s_lshl_b32 s61, s48, 10
	s_ashr_i32 s21, s20, 31
	s_add_u32 s20, s18, s20
	s_addc_u32 s21, s19, s21
	s_add_i32 s56, s61, 0
	s_add_i32 m0, s56, 0x10000
	v_lshl_add_u64 v[16:17], s[20:21], 0, v[130:131]
	global_load_lds_dwordx4 v[16:17], off
	s_add_i32 m0, s56, 0x12000
	s_add_u32 s18, s20, 0xb0000
	s_waitcnt lgkmcnt(0)
	v_lshl_add_u64 v[18:19], s[20:21], 0, v[134:135]
	s_addc_u32 s19, s21, 0
	global_load_lds_dwordx4 v[18:19], off
	s_add_i32 m0, s56, 0x14000
	v_lshl_add_u64 v[20:21], s[18:19], 0, v[130:131]
	s_mul_i32 s50, s44, 0x160000
	global_load_lds_dwordx4 v[20:21], off
	s_add_i32 m0, s56, 0x16000
	s_mul_hi_i32 s17, s44, 0x160000
	v_lshl_add_u64 v[22:23], s[18:19], 0, v[134:135]
	s_add_u32 s18, s46, s50
	s_addc_u32 s19, s49, s17
	s_add_i32 s57, s56, 0x2000
	global_load_lds_dwordx4 v[22:23], off
	v_lshl_add_u64 v[24:25], s[18:19], 0, v[128:129]
	s_mov_b32 m0, s56
	s_add_u32 s50, s18, 0xb0000
	global_load_lds_dwordx4 v[24:25], off
	v_lshl_add_u64 v[26:27], s[18:19], 0, v[132:133]
	s_mov_b32 m0, s57
	s_addc_u32 s51, s19, 0
	s_add_i32 s54, s56, 0x4000
	global_load_lds_dwordx4 v[26:27], off
	v_lshl_add_u64 v[12:13], s[50:51], 0, v[128:129]
	s_mov_b32 m0, s54
	s_add_i32 s55, s56, 0x6000
	global_load_lds_dwordx4 v[12:13], off
	v_lshl_add_u64 v[14:15], s[50:51], 0, v[132:133]
	s_mov_b32 m0, s55
	s_cmp_lg_u32 s47, 1
	global_load_lds_dwordx4 v[14:15], off
	s_cbranch_scc1 .LBB0_1107
	s_barrier
	.p2align	6
